# GEMM K-loops: first K-tile peeled with srcC=0 MFMAs, per-tile 128-register accumulator zero-init removed (all three GEMM loops)
# speedup vs baseline: 1.0067x; 1.0067x over previous
; #define PG8_STAGE(bufoff, gbase, voff) do { _Pragma("unroll") for (int _i = 0; _i < 2; ++_i) \
;         __builtin_amdgcn_global_load_lds((const unsigned*)((const char*)(gbase) + (voff)[_i]), (PG8_LAS unsigned*)(lds + (bufoff) + ldsw + _i * 8192), 16, 0, 0); } while (0)
; #define PG8_LDA(dst, b, h) do { _Pragma("unroll") for (int m = 0; m < 4; ++m) _Pragma("unroll") for (int k = 0; k < 2; ++k) dst[m][k] = *(const PG8_LAS bf16x8*)(lds + PG8_SA(b, h) + aoff + m * 2048 + k * 1024); } while (0)
; #define PG8_LDB(dst, b, h) do { _Pragma("unroll") for (int n = 0; n < 2; ++n) _Pragma("unroll") for (int k = 0; k < 2; ++k) dst[n][k] = *(const PG8_LAS bf16x8*)(lds + PG8_SB(b, h) + boff + n * 2048 + k * 1024); } while (0)
; #define PG8_MMA(ai, bj, At, Bt) do { __builtin_amdgcn_s_setprio(1); _Pragma("unroll") for (int m = 0; m < 4; ++m) _Pragma("unroll") for (int n = 0; n < 2; ++n) _Pragma("unroll") for (int k = 0; k < 2; ++k) \
;         acc[ai][bj][m][n] = __builtin_amdgcn_mfma_f32_16x16x32_bf16(Bt[n][k], At[m][k], acc[ai][bj][m][n], 0, 0, 0); __builtin_amdgcn_s_setprio(0); } while (0)
; #define PG8_WAIT_V(n) asm volatile("s_waitcnt vmcnt(" #n ")" ::: "memory")
; #define PG8_WAIT_L(n) asm volatile("s_waitcnt lgkmcnt(" #n ")" ::: "memory")
; template <class Epi, class Sched, bool ALIGN_EPI = false, bool SP2 = false>
; __device__ __forceinline__ void gemm_phase(PG8_LAS unsigned char* lds, const Gemm g, const Sched& S, const Epi& E, const int tid) {
;     ...
;         const bool has_next = S.next(ui + 1, nxt);
;         const char* nA = has_next ? (const char*)g.A + (size_t)nxt.pm * tstep : cA; const char* nB = has_next ? (const char*)g.Bt + (size_t)nxt.pn * tstep : cB;
;         for (int t = 0; t < nt; t += 2) {
;             const bool last = (t == nt - 2);
;             const char* a1 = cA + (size_t)(t + 1) * kstep;
;             const char* a2 = last ? nA : cA + (size_t)(t + 2) * kstep; const char* b2 = last ? nB : cB + (size_t)(t + 2) * kstep;
;             const char* a3 = a2 + kstep; const char* b3 = b2 + kstep;
;             if (last && has_next) S.a_ready(nxt);
;             if constexpr (SP2) {
;             PG8_LDB(B0, 0, 0); PG8_LDB(B1, 0, 1); PG8_SCHED; PG8_LDA(At, 0, 0); PG8_STAGE(PG8_SA(1, 1), a1 + hstep, voffA);
;             PG8_WAIT_V(8); PG8_WAIT_L(0); PG8_BAR; PG8_MMA(0, 0, At, B0); PG8_MMA(0, 1, At, B1); PG8_BAR; PG8_SCHED;
.LBB0_149:
	s_ashr_i32 s85, s84, 31
	s_lshl_b64 s[6:7], s[84:85], 19
	s_add_u32 s56, s88, s6
	s_addc_u32 s57, s89, s7
	s_and_b64 s[6:7], s[8:9], exec
	s_cselect_b32 s1, s57, s11
	s_cselect_b32 s6, s56, s10
	s_ashr_i32 s53, s52, 31
	s_lshl_b64 s[12:13], s[52:53], 19
	s_add_u32 s58, s82, s12
	s_addc_u32 s59, s43, s13
	s_and_b64 s[12:13], s[8:9], exec
	s_cselect_b32 s7, s59, s3
	s_cselect_b32 s14, s58, s2
	s_add_u32 s15, s2, 0x100
	s_addc_u32 s16, s3, 0
	s_add_u32 s2, s10, 0x40080
	s_addc_u32 s3, s11, 0
	s_mov_b32 s17, -2
	s_add_u32 s10, s2, 0xfffc0080
	s_addc_u32 s11, s3, -1
	s_add_i32 s20, 0, 0x10000
	s_cmp_eq_u32 s17, 12
	s_cselect_b32 s13, s1, s11
	s_cselect_b32 s12, s6, s10
	s_cselect_b32 s11, s7, s16
	s_cselect_b32 s10, s14, s15
	s_add_i32 s53, 0, 0x14000
	v_add_u32_e32 v140, s20, v162
	v_add_u32_e32 v164, s53, v162
	ds_read_b128 v[128:131], v140
	ds_read_b128 v[132:135], v140 offset:1024
	ds_read_b128 v[136:139], v140 offset:2048
	ds_read_b128 v[140:143], v140 offset:3072
	ds_read_b128 v[156:159], v164
	ds_read_b128 v[180:183], v164 offset:1024
	ds_read_b128 v[184:187], v164 offset:2048
	ds_read_b128 v[188:191], v164 offset:3072
	v_lshl_add_u64 v[166:167], s[2:3], 0, v[154:155]
	s_add_i32 m0, s51, 0xc000
	ds_read_b128 v[192:195], v163
	ds_read_b128 v[196:199], v163 offset:1024
	ds_read_b128 v[214:217], v163 offset:2048
	ds_read_b128 v[218:221], v163 offset:3072
	ds_read_b128 v[222:225], v163 offset:4096
	ds_read_b128 v[226:229], v163 offset:5120
	ds_read_b128 v[230:233], v163 offset:6144
	ds_read_b128 v[234:237], v163 offset:7168
	global_load_lds_dwordx4 v[166:167], off
	v_lshl_add_u64 v[166:167], s[2:3], 0, v[152:153]
	s_add_i32 m0, s51, 0xe000
	s_nop 0
	global_load_lds_dwordx4 v[166:167], off
	s_waitcnt vmcnt(8)
	s_waitcnt lgkmcnt(0)
	s_barrier
	s_waitcnt lgkmcnt(0)
	v_mfma_f32_16x16x32_bf16 v[120:123], v[128:131], v[192:195], 0
	v_mfma_f32_16x16x32_bf16 v[124:127], v[136:139], v[192:195], 0
	v_mfma_f32_16x16x32_bf16 v[112:115], v[128:131], v[214:217], 0
	v_mfma_f32_16x16x32_bf16 v[116:119], v[136:139], v[214:217], 0
	v_mfma_f32_16x16x32_bf16 v[104:107], v[128:131], v[222:225], 0
	v_mfma_f32_16x16x32_bf16 v[108:111], v[136:139], v[222:225], 0
	v_mfma_f32_16x16x32_bf16 v[96:99], v[128:131], v[230:233], 0
	v_mfma_f32_16x16x32_bf16 v[100:103], v[136:139], v[230:233], 0
	v_mfma_f32_16x16x32_bf16 v[120:123], v[132:135], v[196:199], v[120:123]
	v_mfma_f32_16x16x32_bf16 v[124:127], v[140:143], v[196:199], v[124:127]
	v_mfma_f32_16x16x32_bf16 v[112:115], v[132:135], v[218:221], v[112:115]
	v_mfma_f32_16x16x32_bf16 v[116:119], v[140:143], v[218:221], v[116:119]
	v_mfma_f32_16x16x32_bf16 v[104:107], v[132:135], v[226:229], v[104:107]
	v_mfma_f32_16x16x32_bf16 v[108:111], v[140:143], v[226:229], v[108:111]
	v_mfma_f32_16x16x32_bf16 v[96:99], v[132:135], v[234:237], v[96:99]
	v_mfma_f32_16x16x32_bf16 v[100:103], v[140:143], v[234:237], v[100:103]
	v_mfma_f32_16x16x32_bf16 v[56:59], v[156:159], v[192:195], 0
	v_mfma_f32_16x16x32_bf16 v[60:63], v[184:187], v[192:195], 0
	v_mfma_f32_16x16x32_bf16 v[48:51], v[156:159], v[214:217], 0
	v_mfma_f32_16x16x32_bf16 v[52:55], v[184:187], v[214:217], 0
	v_mfma_f32_16x16x32_bf16 v[40:43], v[156:159], v[222:225], 0
	v_mfma_f32_16x16x32_bf16 v[44:47], v[184:187], v[222:225], 0
	v_mfma_f32_16x16x32_bf16 v[32:35], v[156:159], v[230:233], 0
	v_mfma_f32_16x16x32_bf16 v[36:39], v[184:187], v[230:233], 0
	v_mfma_f32_16x16x32_bf16 v[56:59], v[180:183], v[196:199], v[56:59]
	v_mfma_f32_16x16x32_bf16 v[60:63], v[188:191], v[196:199], v[60:63]
	v_mfma_f32_16x16x32_bf16 v[48:51], v[180:183], v[218:221], v[48:51]
	v_mfma_f32_16x16x32_bf16 v[52:55], v[188:191], v[218:221], v[52:55]
	v_mfma_f32_16x16x32_bf16 v[40:43], v[180:183], v[226:229], v[40:43]
	v_mfma_f32_16x16x32_bf16 v[44:47], v[188:191], v[226:229], v[44:47]
	v_mfma_f32_16x16x32_bf16 v[32:35], v[180:183], v[234:237], v[32:35]
	v_mfma_f32_16x16x32_bf16 v[36:39], v[188:191], v[234:237], v[36:39]
	s_barrier
; #define PG8_STAGE(bufoff, gbase, voff) do { _Pragma("unroll") for (int _i = 0; _i < 2; ++_i) \
;         __builtin_amdgcn_global_load_lds((const unsigned*)((const char*)(gbase) + (voff)[_i]), (PG8_LAS unsigned*)(lds + (bufoff) + ldsw + _i * 8192), 16, 0, 0); } while (0)
; #define PG8_LDA(dst, b, h) do { _Pragma("unroll") for (int m = 0; m < 4; ++m) _Pragma("unroll") for (int k = 0; k < 2; ++k) dst[m][k] = *(const PG8_LAS bf16x8*)(lds + PG8_SA(b, h) + aoff + m * 2048 + k * 1024); } while (0)
; #define PG8_MMA(ai, bj, At, Bt) do { __builtin_amdgcn_s_setprio(1); _Pragma("unroll") for (int m = 0; m < 4; ++m) _Pragma("unroll") for (int n = 0; n < 2; ++n) _Pragma("unroll") for (int k = 0; k < 2; ++k) \
;         acc[ai][bj][m][n] = __builtin_amdgcn_mfma_f32_16x16x32_bf16(Bt[n][k], At[m][k], acc[ai][bj][m][n], 0, 0, 0); __builtin_amdgcn_s_setprio(0); } while (0)
; #define PG8_WAIT_V(n) asm volatile("s_waitcnt vmcnt(" #n ")" ::: "memory")
; #define PG8_WAIT_L(n) asm volatile("s_waitcnt lgkmcnt(" #n ")" ::: "memory")
; #define PG8_BAR __builtin_amdgcn_s_barrier()
; #define PG8_SCHED __builtin_amdgcn_sched_barrier(0)
; template <class Epi, class Sched, bool ALIGN_EPI = false, bool SP2 = false>
; __device__ __forceinline__ void gemm_phase(PG8_LAS unsigned char* lds, const Gemm g, const Sched& S, const Epi& E, const int tid) {
;     ...
;             PG8_LDA(At, 0, 1); PG8_STAGE(PG8_SB(0, 0), b2, voffB); PG8_STAGE(PG8_SB(0, 1), b2 + hstep, voffB); PG8_STAGE(PG8_SA(0, 0), a2, voffA);
;             PG8_WAIT_V(8); PG8_WAIT_L(0); PG8_BAR; PG8_MMA(1, 0, At, B0); PG8_MMA(1, 1, At, B1); PG8_BAR; PG8_SCHED;
	s_add_i32 s20, s20, s50
	v_lshl_add_u64 v[166:167], s[10:11], 0, v[146:147]
	s_mov_b32 m0, s20
	ds_read_b128 v[192:195], v163 offset:16384
	ds_read_b128 v[196:199], v163 offset:17408
	ds_read_b128 v[214:217], v163 offset:18432
	ds_read_b128 v[218:221], v163 offset:19456
	ds_read_b128 v[222:225], v163 offset:20480
	ds_read_b128 v[226:229], v163 offset:21504
	ds_read_b128 v[230:233], v163 offset:22528
	ds_read_b128 v[234:237], v163 offset:23552
	global_load_lds_dwordx4 v[166:167], off
	s_add_i32 m0, s20, 0x2000
	s_add_u32 s20, s10, 0x40000
	v_lshl_add_u64 v[200:201], s[10:11], 0, v[150:151]
	s_addc_u32 s21, s11, 0
	s_add_i32 s53, s53, s50
	global_load_lds_dwordx4 v[200:201], off
	v_lshl_add_u64 v[238:239], s[20:21], 0, v[146:147]
	s_mov_b32 m0, s53
	v_lshl_add_u64 v[240:241], s[12:13], 0, v[148:149]
	global_load_lds_dwordx4 v[238:239], off
	v_lshl_add_u64 v[238:239], s[20:21], 0, v[150:151]
	s_add_i32 m0, s53, 0x2000
	s_nop 0
	global_load_lds_dwordx4 v[238:239], off
	v_lshl_add_u64 v[238:239], s[12:13], 0, v[144:145]
	s_mov_b32 m0, s51
	s_nop 0
	global_load_lds_dwordx4 v[238:239], off
	s_mov_b32 m0, s55
	s_nop 0
	global_load_lds_dwordx4 v[240:241], off
	s_waitcnt vmcnt(8)
	s_waitcnt lgkmcnt(0)
	s_barrier
	s_waitcnt lgkmcnt(0)
	v_mfma_f32_16x16x32_bf16 v[88:91], v[128:131], v[192:195], 0
	v_mfma_f32_16x16x32_bf16 v[92:95], v[136:139], v[192:195], 0
	v_mfma_f32_16x16x32_bf16 v[80:83], v[128:131], v[214:217], 0
	v_mfma_f32_16x16x32_bf16 v[84:87], v[136:139], v[214:217], 0
	v_mfma_f32_16x16x32_bf16 v[72:75], v[128:131], v[222:225], 0
	v_mfma_f32_16x16x32_bf16 v[76:79], v[136:139], v[222:225], 0
	v_mfma_f32_16x16x32_bf16 v[64:67], v[128:131], v[230:233], 0
	v_mfma_f32_16x16x32_bf16 v[68:71], v[136:139], v[230:233], 0
	v_mfma_f32_16x16x32_bf16 v[88:91], v[132:135], v[196:199], v[88:91]
	v_mfma_f32_16x16x32_bf16 v[92:95], v[140:143], v[196:199], v[92:95]
	v_mfma_f32_16x16x32_bf16 v[80:83], v[132:135], v[218:221], v[80:83]
	v_mfma_f32_16x16x32_bf16 v[84:87], v[140:143], v[218:221], v[84:87]
	v_mfma_f32_16x16x32_bf16 v[72:75], v[132:135], v[226:229], v[72:75]
	v_mfma_f32_16x16x32_bf16 v[76:79], v[140:143], v[226:229], v[76:79]
	v_mfma_f32_16x16x32_bf16 v[64:67], v[132:135], v[234:237], v[64:67]
	v_mfma_f32_16x16x32_bf16 v[68:71], v[140:143], v[234:237], v[68:71]
	v_mfma_f32_16x16x32_bf16 v[24:27], v[156:159], v[192:195], 0
	v_mfma_f32_16x16x32_bf16 v[28:31], v[184:187], v[192:195], 0
	v_mfma_f32_16x16x32_bf16 v[16:19], v[156:159], v[214:217], 0
	v_mfma_f32_16x16x32_bf16 v[20:23], v[184:187], v[214:217], 0
	v_mfma_f32_16x16x32_bf16 v[8:11], v[156:159], v[222:225], 0
	v_mfma_f32_16x16x32_bf16 v[12:15], v[184:187], v[222:225], 0
	v_mfma_f32_16x16x32_bf16 v[4:7], v[156:159], v[230:233], 0
	v_mfma_f32_16x16x32_bf16 v[0:3], v[184:187], v[230:233], 0
	v_mfma_f32_16x16x32_bf16 v[24:27], v[180:183], v[196:199], v[24:27]
	v_mfma_f32_16x16x32_bf16 v[28:31], v[188:191], v[196:199], v[28:31]
	v_mfma_f32_16x16x32_bf16 v[16:19], v[180:183], v[218:221], v[16:19]
	v_mfma_f32_16x16x32_bf16 v[20:23], v[188:191], v[218:221], v[20:23]
	v_mfma_f32_16x16x32_bf16 v[8:11], v[180:183], v[226:229], v[8:11]
	v_mfma_f32_16x16x32_bf16 v[12:15], v[188:191], v[226:229], v[12:15]
	v_mfma_f32_16x16x32_bf16 v[4:7], v[180:183], v[234:237], v[4:7]
	v_mfma_f32_16x16x32_bf16 v[0:3], v[188:191], v[234:237], v[0:3]
	s_barrier
	s_branch .Lmix_mid

; #define PG8_STAGE(bufoff, gbase, voff) do { _Pragma("unroll") for (int _i = 0; _i < 2; ++_i) \
;         __builtin_amdgcn_global_load_lds((const unsigned*)((const char*)(gbase) + (voff)[_i]), (PG8_LAS unsigned*)(lds + (bufoff) + ldsw + _i * 8192), 16, 0, 0); } while (0)
; #define PG8_LDA(dst, b, h) do { _Pragma("unroll") for (int m = 0; m < 4; ++m) _Pragma("unroll") for (int k = 0; k < 2; ++k) dst[m][k] = *(const PG8_LAS bf16x8*)(lds + PG8_SA(b, h) + aoff + m * 2048 + k * 1024); } while (0)
; #define PG8_LDB(dst, b, h) do { _Pragma("unroll") for (int n = 0; n < 2; ++n) _Pragma("unroll") for (int k = 0; k < 2; ++k) dst[n][k] = *(const PG8_LAS bf16x8*)(lds + PG8_SB(b, h) + boff + n * 2048 + k * 1024); } while (0)
; #define PG8_MMA(ai, bj, At, Bt) do { __builtin_amdgcn_s_setprio(1); _Pragma("unroll") for (int m = 0; m < 4; ++m) _Pragma("unroll") for (int n = 0; n < 2; ++n) _Pragma("unroll") for (int k = 0; k < 2; ++k) \
;         acc[ai][bj][m][n] = __builtin_amdgcn_mfma_f32_16x16x32_bf16(Bt[n][k], At[m][k], acc[ai][bj][m][n], 0, 0, 0); __builtin_amdgcn_s_setprio(0); } while (0)
; #define PG8_WAIT_V(n) asm volatile("s_waitcnt vmcnt(" #n ")" ::: "memory")
; #define PG8_WAIT_L(n) asm volatile("s_waitcnt lgkmcnt(" #n ")" ::: "memory")
; #define PG8_BAR __builtin_amdgcn_s_barrier()
; #define PG8_SCHED __builtin_amdgcn_sched_barrier(0)
; template <class Epi, class Sched, bool ALIGN_EPI = false, bool SP2 = false>
; __device__ __forceinline__ void gemm_phase(PG8_LAS unsigned char* lds, const Gemm g, const Sched& S, const Epi& E, const int tid) {
;     ...
;             PG8_LDB(B0, 1, 0); PG8_LDB(B1, 1, 1); PG8_SCHED; PG8_LDA(At, 1, 0); PG8_STAGE(PG8_SA(0, 1), a2 + hstep, voffA);
;             PG8_WAIT_V(8); PG8_WAIT_L(0); PG8_BAR; PG8_MMA(0, 0, At, B0); PG8_MMA(0, 1, At, B1); PG8_BAR; PG8_SCHED;
.Lmix_mid:
	s_add_i32 s20, 0, 0x18000
	s_add_i32 s21, 0, 0x1c000
	v_add_u32_e32 v140, s20, v162
	v_add_u32_e32 v164, s21, v162
	ds_read_b128 v[128:131], v140
	ds_read_b128 v[132:135], v140 offset:1024
	ds_read_b128 v[136:139], v140 offset:2048
	ds_read_b128 v[140:143], v140 offset:3072
	ds_read_b128 v[156:159], v164
	ds_read_b128 v[180:183], v164 offset:1024
	ds_read_b128 v[184:187], v164 offset:2048
	ds_read_b128 v[188:191], v164 offset:3072
	s_add_u32 s12, s12, 0x40000
	s_addc_u32 s13, s13, 0
	s_mov_b32 m0, s81
	v_lshl_add_u64 v[242:243], s[12:13], 0, v[144:145]
	ds_read_b128 v[192:195], v163 offset:32768
	ds_read_b128 v[196:199], v163 offset:33792
	ds_read_b128 v[214:217], v163 offset:34816
	ds_read_b128 v[218:221], v163 offset:35840
	ds_read_b128 v[222:225], v163 offset:36864
	ds_read_b128 v[226:229], v163 offset:37888
	ds_read_b128 v[230:233], v163 offset:38912
	ds_read_b128 v[234:237], v163 offset:39936
	global_load_lds_dwordx4 v[242:243], off
	v_lshl_add_u64 v[242:243], s[12:13], 0, v[148:149]
	s_mov_b32 m0, s38
	s_nop 0
	global_load_lds_dwordx4 v[242:243], off
	s_waitcnt vmcnt(8)
	s_waitcnt lgkmcnt(0)
	s_barrier
	s_waitcnt lgkmcnt(0)
	v_mfma_f32_16x16x32_bf16 v[120:123], v[128:131], v[192:195], v[120:123]
	v_mfma_f32_16x16x32_bf16 v[124:127], v[136:139], v[192:195], v[124:127]
	v_mfma_f32_16x16x32_bf16 v[112:115], v[128:131], v[214:217], v[112:115]
	v_mfma_f32_16x16x32_bf16 v[116:119], v[136:139], v[214:217], v[116:119]
	v_mfma_f32_16x16x32_bf16 v[104:107], v[128:131], v[222:225], v[104:107]
	v_mfma_f32_16x16x32_bf16 v[108:111], v[136:139], v[222:225], v[108:111]
	v_mfma_f32_16x16x32_bf16 v[96:99], v[128:131], v[230:233], v[96:99]
	v_mfma_f32_16x16x32_bf16 v[100:103], v[136:139], v[230:233], v[100:103]
	v_mfma_f32_16x16x32_bf16 v[120:123], v[132:135], v[196:199], v[120:123]
	v_mfma_f32_16x16x32_bf16 v[124:127], v[140:143], v[196:199], v[124:127]
	v_mfma_f32_16x16x32_bf16 v[112:115], v[132:135], v[218:221], v[112:115]
	v_mfma_f32_16x16x32_bf16 v[116:119], v[140:143], v[218:221], v[116:119]
	v_mfma_f32_16x16x32_bf16 v[104:107], v[132:135], v[226:229], v[104:107]
	v_mfma_f32_16x16x32_bf16 v[108:111], v[140:143], v[226:229], v[108:111]
	v_mfma_f32_16x16x32_bf16 v[96:99], v[132:135], v[234:237], v[96:99]
	v_mfma_f32_16x16x32_bf16 v[100:103], v[140:143], v[234:237], v[100:103]
	v_mfma_f32_16x16x32_bf16 v[56:59], v[156:159], v[192:195], v[56:59]
	v_mfma_f32_16x16x32_bf16 v[60:63], v[184:187], v[192:195], v[60:63]
	v_mfma_f32_16x16x32_bf16 v[48:51], v[156:159], v[214:217], v[48:51]
	v_mfma_f32_16x16x32_bf16 v[52:55], v[184:187], v[214:217], v[52:55]
	v_mfma_f32_16x16x32_bf16 v[40:43], v[156:159], v[222:225], v[40:43]
	v_mfma_f32_16x16x32_bf16 v[44:47], v[184:187], v[222:225], v[44:47]
	v_mfma_f32_16x16x32_bf16 v[32:35], v[156:159], v[230:233], v[32:35]
	v_mfma_f32_16x16x32_bf16 v[36:39], v[184:187], v[230:233], v[36:39]
	v_mfma_f32_16x16x32_bf16 v[56:59], v[180:183], v[196:199], v[56:59]
	v_mfma_f32_16x16x32_bf16 v[60:63], v[188:191], v[196:199], v[60:63]
	v_mfma_f32_16x16x32_bf16 v[48:51], v[180:183], v[218:221], v[48:51]
	v_mfma_f32_16x16x32_bf16 v[52:55], v[188:191], v[218:221], v[52:55]
	v_mfma_f32_16x16x32_bf16 v[40:43], v[180:183], v[226:229], v[40:43]
	v_mfma_f32_16x16x32_bf16 v[44:47], v[188:191], v[226:229], v[44:47]
	v_mfma_f32_16x16x32_bf16 v[32:35], v[180:183], v[234:237], v[32:35]
	v_mfma_f32_16x16x32_bf16 v[36:39], v[188:191], v[234:237], v[36:39]
	s_barrier
; #define PG8_STAGE(bufoff, gbase, voff) do { _Pragma("unroll") for (int _i = 0; _i < 2; ++_i) \
;         __builtin_amdgcn_global_load_lds((const unsigned*)((const char*)(gbase) + (voff)[_i]), (PG8_LAS unsigned*)(lds + (bufoff) + ldsw + _i * 8192), 16, 0, 0); } while (0)
; #define PG8_LDA(dst, b, h) do { _Pragma("unroll") for (int m = 0; m < 4; ++m) _Pragma("unroll") for (int k = 0; k < 2; ++k) dst[m][k] = *(const PG8_LAS bf16x8*)(lds + PG8_SA(b, h) + aoff + m * 2048 + k * 1024); } while (0)
; #define PG8_MMA(ai, bj, At, Bt) do { __builtin_amdgcn_s_setprio(1); _Pragma("unroll") for (int m = 0; m < 4; ++m) _Pragma("unroll") for (int n = 0; n < 2; ++n) _Pragma("unroll") for (int k = 0; k < 2; ++k) \
;         acc[ai][bj][m][n] = __builtin_amdgcn_mfma_f32_16x16x32_bf16(Bt[n][k], At[m][k], acc[ai][bj][m][n], 0, 0, 0); __builtin_amdgcn_s_setprio(0); } while (0)
; #define PG8_WAIT_V(n) asm volatile("s_waitcnt vmcnt(" #n ")" ::: "memory")
; #define PG8_WAIT_L(n) asm volatile("s_waitcnt lgkmcnt(" #n ")" ::: "memory")
; #define PG8_BAR __builtin_amdgcn_s_barrier()
; #define PG8_SCHED __builtin_amdgcn_sched_barrier(0)
; template <class Epi, class Sched, bool ALIGN_EPI = false, bool SP2 = false>
; __device__ __forceinline__ void gemm_phase(PG8_LAS unsigned char* lds, const Gemm g, const Sched& S, const Epi& E, const int tid) {
;     ...
;             PG8_LDA(At, 1, 1); PG8_STAGE(PG8_SB(1, 0), b3, voffB); PG8_STAGE(PG8_SB(1, 1), b3 + hstep, voffB); PG8_STAGE(PG8_SA(1, 0), a3, voffA);
;             PG8_WAIT_V(8); PG8_WAIT_L(0); PG8_BAR; PG8_MMA(1, 0, At, B0); PG8_MMA(1, 1, At, B1); PG8_BAR; PG8_SCHED;
;     ...
;         if constexpr (ALIGN_EPI) { if (wr == 0) PG8_BAR; }
	s_add_i32 s12, s20, s50
	v_lshl_add_u64 v[166:167], v[166:167], 0, s[86:87]
	s_mov_b32 m0, s12
	ds_read_b128 v[192:195], v163 offset:49152
	ds_read_b128 v[196:199], v163 offset:50176
	ds_read_b128 v[214:217], v163 offset:51200
	ds_read_b128 v[218:221], v163 offset:52224
	ds_read_b128 v[222:225], v163 offset:53248
	ds_read_b128 v[226:229], v163 offset:54272
	ds_read_b128 v[230:233], v163 offset:55296
	ds_read_b128 v[234:237], v163 offset:56320
	global_load_lds_dwordx4 v[166:167], off
	s_add_i32 m0, s12, 0x2000
	s_add_u32 s10, s10, 0x40080
	v_lshl_add_u64 v[166:167], v[200:201], 0, s[86:87]
	s_addc_u32 s11, s11, 0
	s_add_i32 s12, s21, s50
	global_load_lds_dwordx4 v[166:167], off
	v_lshl_add_u64 v[166:167], s[10:11], 0, v[146:147]
	s_mov_b32 m0, s12
	s_nop 0
	global_load_lds_dwordx4 v[166:167], off
	v_lshl_add_u64 v[166:167], s[10:11], 0, v[150:151]
	s_add_i32 m0, s12, 0x2000
	s_nop 0
	global_load_lds_dwordx4 v[166:167], off
	v_lshl_add_u64 v[166:167], v[238:239], 0, s[86:87]
	s_mov_b32 m0, s37
	s_nop 0
	global_load_lds_dwordx4 v[166:167], off
	v_lshl_add_u64 v[166:167], v[240:241], 0, s[86:87]
	s_mov_b32 m0, s41
	s_nop 0
	global_load_lds_dwordx4 v[166:167], off
	s_waitcnt vmcnt(8)
	s_waitcnt lgkmcnt(0)
	s_barrier
	s_waitcnt lgkmcnt(0)
	v_mfma_f32_16x16x32_bf16 v[88:91], v[128:131], v[192:195], v[88:91]
	v_mfma_f32_16x16x32_bf16 v[92:95], v[136:139], v[192:195], v[92:95]
	v_mfma_f32_16x16x32_bf16 v[80:83], v[128:131], v[214:217], v[80:83]
	v_mfma_f32_16x16x32_bf16 v[84:87], v[136:139], v[214:217], v[84:87]
	v_mfma_f32_16x16x32_bf16 v[72:75], v[128:131], v[222:225], v[72:75]
	v_mfma_f32_16x16x32_bf16 v[76:79], v[136:139], v[222:225], v[76:79]
	v_mfma_f32_16x16x32_bf16 v[64:67], v[128:131], v[230:233], v[64:67]
	v_mfma_f32_16x16x32_bf16 v[68:71], v[136:139], v[230:233], v[68:71]
	v_mfma_f32_16x16x32_bf16 v[88:91], v[132:135], v[196:199], v[88:91]
	v_mfma_f32_16x16x32_bf16 v[92:95], v[140:143], v[196:199], v[92:95]
	v_mfma_f32_16x16x32_bf16 v[80:83], v[132:135], v[218:221], v[80:83]
	v_mfma_f32_16x16x32_bf16 v[84:87], v[140:143], v[218:221], v[84:87]
	v_mfma_f32_16x16x32_bf16 v[72:75], v[132:135], v[226:229], v[72:75]
	v_mfma_f32_16x16x32_bf16 v[76:79], v[140:143], v[226:229], v[76:79]
	v_mfma_f32_16x16x32_bf16 v[64:67], v[132:135], v[234:237], v[64:67]
	v_mfma_f32_16x16x32_bf16 v[68:71], v[140:143], v[234:237], v[68:71]
	v_mfma_f32_16x16x32_bf16 v[24:27], v[156:159], v[192:195], v[24:27]
	v_mfma_f32_16x16x32_bf16 v[28:31], v[184:187], v[192:195], v[28:31]
	v_mfma_f32_16x16x32_bf16 v[16:19], v[156:159], v[214:217], v[16:19]
	v_mfma_f32_16x16x32_bf16 v[20:23], v[184:187], v[214:217], v[20:23]
	v_mfma_f32_16x16x32_bf16 v[8:11], v[156:159], v[222:225], v[8:11]
	v_mfma_f32_16x16x32_bf16 v[12:15], v[184:187], v[222:225], v[12:15]
	v_mfma_f32_16x16x32_bf16 v[4:7], v[156:159], v[230:233], v[4:7]
	v_mfma_f32_16x16x32_bf16 v[0:3], v[184:187], v[230:233], v[0:3]
	v_mfma_f32_16x16x32_bf16 v[24:27], v[180:183], v[196:199], v[24:27]
	v_mfma_f32_16x16x32_bf16 v[28:31], v[188:191], v[196:199], v[28:31]
	v_mfma_f32_16x16x32_bf16 v[16:19], v[180:183], v[218:221], v[16:19]
	v_mfma_f32_16x16x32_bf16 v[20:23], v[188:191], v[218:221], v[20:23]
	v_mfma_f32_16x16x32_bf16 v[8:11], v[180:183], v[226:229], v[8:11]
	v_mfma_f32_16x16x32_bf16 v[12:15], v[188:191], v[226:229], v[12:15]
	v_mfma_f32_16x16x32_bf16 v[4:7], v[180:183], v[234:237], v[4:7]
	v_mfma_f32_16x16x32_bf16 v[0:3], v[188:191], v[234:237], v[0:3]
	s_barrier
	s_add_i32 s17, s17, 2
	s_add_u32 s15, s15, 0x100
	s_addc_u32 s16, s16, 0
	s_add_u32 s2, s2, 0x100
	s_addc_u32 s3, s3, 0
	s_cmp_gt_u32 s17, 13
	s_cbranch_scc0 .LBB0_150
	v_readlane_b32 s2, v255, 13
	v_readlane_b32 s3, v255, 14
	s_and_b64 vcc, exec, s[2:3]
	s_cbranch_vccz .LBB0_153
	s_barrier

; #define PG8_STAGE(bufoff, gbase, voff) do { _Pragma("unroll") for (int _i = 0; _i < 2; ++_i) \
;         __builtin_amdgcn_global_load_lds((const unsigned*)((const char*)(gbase) + (voff)[_i]), (PG8_LAS unsigned*)(lds + (bufoff) + ldsw + _i * 8192), 16, 0, 0); } while (0)
; #define PG8_LDA(dst, b, h) do { _Pragma("unroll") for (int m = 0; m < 4; ++m) _Pragma("unroll") for (int k = 0; k < 2; ++k) dst[m][k] = *(const PG8_LAS bf16x8*)(lds + PG8_SA(b, h) + aoff + m * 2048 + k * 1024); } while (0)
; #define PG8_LDB(dst, b, h) do { _Pragma("unroll") for (int n = 0; n < 2; ++n) _Pragma("unroll") for (int k = 0; k < 2; ++k) dst[n][k] = *(const PG8_LAS bf16x8*)(lds + PG8_SB(b, h) + boff + n * 2048 + k * 1024); } while (0)
; #define PG8_WAIT_V(n) asm volatile("s_waitcnt vmcnt(" #n ")" ::: "memory")
; #define PG8_WAIT_L(n) asm volatile("s_waitcnt lgkmcnt(" #n ")" ::: "memory")
; #define PG8_BAR __builtin_amdgcn_s_barrier()
; #define PG8_SCHED __builtin_amdgcn_sched_barrier(0)
; template <class Epi, class Sched, bool ALIGN_EPI = false, bool SP2 = false>
; __device__ __forceinline__ void gemm_phase(PG8_LAS unsigned char* lds, const Gemm g, const Sched& S, const Epi& E, const int tid) {
;     ...
;         const bool has_next = S.next(ui + 1, nxt);
;         const char* nA = has_next ? (const char*)g.A + (size_t)nxt.pm * tstep : cA; const char* nB = has_next ? (const char*)g.Bt + (size_t)nxt.pn * tstep : cB;
;         for (int t = 0; t < nt; t += 2) {
;             const bool last = (t == nt - 2);
;             const char* a1 = cA + (size_t)(t + 1) * kstep;
;             const char* a2 = last ? nA : cA + (size_t)(t + 2) * kstep; const char* b2 = last ? nB : cB + (size_t)(t + 2) * kstep;
;             const char* a3 = a2 + kstep; const char* b3 = b2 + kstep;
;             if (last && has_next) S.a_ready(nxt);
;             if constexpr (SP2) {
;             PG8_LDB(B0, 0, 0); PG8_LDB(B1, 0, 1); PG8_SCHED; PG8_LDA(At, 0, 0); PG8_STAGE(PG8_SA(1, 1), a1 + hstep, voffA);
;             PG8_WAIT_V(8); PG8_WAIT_L(0); PG8_BAR; PG8_MMA(0, 0, At, B0); PG8_MMA(0, 1, At, B1); PG8_BAR; PG8_SCHED;
;             PG8_LDA(At, 0, 1); PG8_STAGE(PG8_SB(0, 0), b2, voffB); PG8_STAGE(PG8_SB(0, 1), b2 + hstep, voffB); PG8_STAGE(PG8_SA(0, 0), a2, voffA);
;             PG8_WAIT_V(8); PG8_WAIT_L(0); PG8_BAR; PG8_MMA(1, 0, At, B0); PG8_MMA(1, 1, At, B1); PG8_BAR; PG8_SCHED;
.LBB0_1304:
	s_add_u32 s73, s8, 0x100
	s_addc_u32 s81, s9, 0
	s_add_u32 s8, s54, 0x80
	s_addc_u32 s9, s55, 0
	s_mov_b32 s54, 0
	s_add_i32 s84, s54, 2
	s_add_u32 s85, s8, 0x80
	s_addc_u32 s55, s9, 0
	s_add_i32 s82, 0, 0x10000
	s_cmp_eq_u32 s62, s54
	s_cselect_b32 s55, s1, s55
	s_cselect_b32 s54, s0, s85
	s_cselect_b32 vcc_hi, s21, s81
	s_cselect_b32 vcc_lo, s20, s73
	s_add_i32 s85, 0, 0x14000
	v_add_u32_e32 v52, s82, v181
	v_add_u32_e32 v156, s85, v181
	ds_read_b128 v[32:35], v52
	ds_read_b128 v[36:39], v52 offset:1024
	ds_read_b128 v[48:51], v52 offset:2048
	ds_read_b128 v[52:55], v52 offset:3072
	ds_read_b128 v[144:147], v156
	ds_read_b128 v[148:151], v156 offset:1024
	ds_read_b128 v[152:155], v156 offset:2048
	ds_read_b128 v[156:159], v156 offset:3072
	v_lshl_add_u64 v[200:201], s[8:9], 0, v[186:187]
	s_add_i32 m0, s45, 0xc000
	ds_read_b128 v[188:191], v218
	ds_read_b128 v[192:195], v218 offset:1024
	ds_read_b128 v[196:199], v218 offset:2048
	ds_read_b128 v[222:225], v218 offset:3072
	ds_read_b128 v[226:229], v218 offset:4096
	ds_read_b128 v[230:233], v218 offset:5120
	ds_read_b128 v[234:237], v218 offset:6144
	ds_read_b128 v[238:241], v218 offset:7168
	global_load_lds_dwordx4 v[200:201], off
	v_lshl_add_u64 v[200:201], s[8:9], 0, v[184:185]
	s_add_i32 m0, s45, 0xe000
	s_nop 0
	global_load_lds_dwordx4 v[200:201], off
	s_waitcnt vmcnt(8)
	s_waitcnt lgkmcnt(0)
	s_barrier
	s_waitcnt lgkmcnt(0)
	v_mfma_f32_16x16x32_bf16 v[140:143], v[32:35], v[188:191], 0
	v_mfma_f32_16x16x32_bf16 v[136:139], v[48:51], v[188:191], 0
	v_mfma_f32_16x16x32_bf16 v[124:127], v[32:35], v[196:199], 0
	v_mfma_f32_16x16x32_bf16 v[120:123], v[48:51], v[196:199], 0
	v_mfma_f32_16x16x32_bf16 v[108:111], v[32:35], v[226:229], 0
	v_mfma_f32_16x16x32_bf16 v[104:107], v[48:51], v[226:229], 0
	v_mfma_f32_16x16x32_bf16 v[92:95], v[32:35], v[234:237], 0
	v_mfma_f32_16x16x32_bf16 v[88:91], v[48:51], v[234:237], 0
	v_mfma_f32_16x16x32_bf16 v[140:143], v[36:39], v[192:195], v[140:143]
	v_mfma_f32_16x16x32_bf16 v[136:139], v[52:55], v[192:195], v[136:139]
	v_mfma_f32_16x16x32_bf16 v[124:127], v[36:39], v[222:225], v[124:127]
	v_mfma_f32_16x16x32_bf16 v[120:123], v[52:55], v[222:225], v[120:123]
	v_mfma_f32_16x16x32_bf16 v[108:111], v[36:39], v[230:233], v[108:111]
	v_mfma_f32_16x16x32_bf16 v[104:107], v[52:55], v[230:233], v[104:107]
	v_mfma_f32_16x16x32_bf16 v[92:95], v[36:39], v[238:241], v[92:95]
	v_mfma_f32_16x16x32_bf16 v[88:91], v[52:55], v[238:241], v[88:91]
	v_mfma_f32_16x16x32_bf16 v[132:135], v[144:147], v[188:191], 0
	v_mfma_f32_16x16x32_bf16 v[128:131], v[152:155], v[188:191], 0
	v_mfma_f32_16x16x32_bf16 v[116:119], v[144:147], v[196:199], 0
	v_mfma_f32_16x16x32_bf16 v[112:115], v[152:155], v[196:199], 0
	v_mfma_f32_16x16x32_bf16 v[100:103], v[144:147], v[226:229], 0
	v_mfma_f32_16x16x32_bf16 v[96:99], v[152:155], v[226:229], 0
	v_mfma_f32_16x16x32_bf16 v[84:87], v[144:147], v[234:237], 0
	v_mfma_f32_16x16x32_bf16 v[80:83], v[152:155], v[234:237], 0
	v_mfma_f32_16x16x32_bf16 v[132:135], v[148:151], v[192:195], v[132:135]
	v_mfma_f32_16x16x32_bf16 v[128:131], v[156:159], v[192:195], v[128:131]
	v_mfma_f32_16x16x32_bf16 v[116:119], v[148:151], v[222:225], v[116:119]
	v_mfma_f32_16x16x32_bf16 v[112:115], v[156:159], v[222:225], v[112:115]
	v_mfma_f32_16x16x32_bf16 v[100:103], v[148:151], v[230:233], v[100:103]
	v_mfma_f32_16x16x32_bf16 v[96:99], v[156:159], v[230:233], v[96:99]
	v_mfma_f32_16x16x32_bf16 v[84:87], v[148:151], v[238:241], v[84:87]
	v_mfma_f32_16x16x32_bf16 v[80:83], v[156:159], v[238:241], v[80:83]
	s_barrier
	s_add_i32 s82, s82, s38
	v_lshl_add_u64 v[200:201], vcc, 0, v[164:165]
	s_mov_b32 m0, s82
	ds_read_b128 v[188:191], v218 offset:16384
	ds_read_b128 v[192:195], v218 offset:17408
	ds_read_b128 v[196:199], v218 offset:18432
	ds_read_b128 v[222:225], v218 offset:19456
	ds_read_b128 v[226:229], v218 offset:20480
	ds_read_b128 v[230:233], v218 offset:21504
	ds_read_b128 v[234:237], v218 offset:22528
	ds_read_b128 v[238:241], v218 offset:23552
	global_load_lds_dwordx4 v[200:201], off
	s_add_i32 m0, s82, 0x2000
	v_lshl_add_u64 v[242:243], vcc, 0, v[160:161]
	s_add_u32 vcc_lo, vcc_lo, s90
	s_addc_u32 vcc_hi, vcc_hi, 0
	s_add_i32 s82, s85, s38
	global_load_lds_dwordx4 v[242:243], off
	v_lshl_add_u64 v[244:245], vcc, 0, v[164:165]
	s_mov_b32 m0, s82
	v_lshl_add_u64 v[246:247], vcc, 0, v[160:161]
	global_load_lds_dwordx4 v[244:245], off
	s_add_i32 m0, s82, 0x2000
	v_lshl_add_u64 v[248:249], s[54:55], 0, v[164:165]
	global_load_lds_dwordx4 v[246:247], off
	s_mov_b32 m0, s45
	v_lshl_add_u64 v[250:251], s[54:55], 0, v[160:161]
	global_load_lds_dwordx4 v[248:249], off
	s_mov_b32 m0, s48
	s_nop 0
	global_load_lds_dwordx4 v[250:251], off
	s_waitcnt vmcnt(8)
	s_waitcnt lgkmcnt(0)
	s_barrier
	s_waitcnt lgkmcnt(0)
	v_mfma_f32_16x16x32_bf16 v[76:79], v[32:35], v[188:191], 0
	v_mfma_f32_16x16x32_bf16 v[72:75], v[48:51], v[188:191], 0
	v_mfma_f32_16x16x32_bf16 v[60:63], v[32:35], v[196:199], 0
	v_mfma_f32_16x16x32_bf16 v[56:59], v[48:51], v[196:199], 0
	v_mfma_f32_16x16x32_bf16 v[28:31], v[32:35], v[226:229], 0
	v_mfma_f32_16x16x32_bf16 v[24:27], v[48:51], v[226:229], 0
	v_mfma_f32_16x16x32_bf16 v[12:15], v[32:35], v[234:237], 0
	v_mfma_f32_16x16x32_bf16 v[8:11], v[48:51], v[234:237], 0
	v_mfma_f32_16x16x32_bf16 v[76:79], v[36:39], v[192:195], v[76:79]
	v_mfma_f32_16x16x32_bf16 v[72:75], v[52:55], v[192:195], v[72:75]
	v_mfma_f32_16x16x32_bf16 v[60:63], v[36:39], v[222:225], v[60:63]
	v_mfma_f32_16x16x32_bf16 v[56:59], v[52:55], v[222:225], v[56:59]
	v_mfma_f32_16x16x32_bf16 v[28:31], v[36:39], v[230:233], v[28:31]
	v_mfma_f32_16x16x32_bf16 v[24:27], v[52:55], v[230:233], v[24:27]
	v_mfma_f32_16x16x32_bf16 v[12:15], v[36:39], v[238:241], v[12:15]
	v_mfma_f32_16x16x32_bf16 v[8:11], v[52:55], v[238:241], v[8:11]
	v_mfma_f32_16x16x32_bf16 v[44:47], v[144:147], v[196:199], 0
	v_mfma_f32_16x16x32_bf16 v[40:43], v[152:155], v[196:199], 0
	v_mfma_f32_16x16x32_bf16 v[20:23], v[144:147], v[226:229], 0
	v_mfma_f32_16x16x32_bf16 v[16:19], v[152:155], v[226:229], 0
	v_mfma_f32_16x16x32_bf16 v[4:7], v[144:147], v[234:237], 0
	v_mfma_f32_16x16x32_bf16 v[0:3], v[152:155], v[234:237], 0
	v_mfma_f32_16x16x32_bf16 v[32:35], v[144:147], v[188:191], 0
	v_mfma_f32_16x16x32_bf16 v[36:39], v[152:155], v[188:191], 0
	v_mfma_f32_16x16x32_bf16 v[44:47], v[148:151], v[222:225], v[44:47]
	v_mfma_f32_16x16x32_bf16 v[40:43], v[156:159], v[222:225], v[40:43]
	v_mfma_f32_16x16x32_bf16 v[20:23], v[148:151], v[230:233], v[20:23]
	v_mfma_f32_16x16x32_bf16 v[16:19], v[156:159], v[230:233], v[16:19]
	v_mfma_f32_16x16x32_bf16 v[4:7], v[148:151], v[238:241], v[4:7]
	v_mfma_f32_16x16x32_bf16 v[0:3], v[156:159], v[238:241], v[0:3]
	v_mfma_f32_16x16x32_bf16 v[32:35], v[148:151], v[192:195], v[32:35]
	v_mfma_f32_16x16x32_bf16 v[36:39], v[156:159], v[192:195], v[36:39]
	s_barrier
	s_branch .Lres_mid

; #define PG8_STAGE(bufoff, gbase, voff) do { _Pragma("unroll") for (int _i = 0; _i < 2; ++_i) \
;         __builtin_amdgcn_global_load_lds((const unsigned*)((const char*)(gbase) + (voff)[_i]), (PG8_LAS unsigned*)(lds + (bufoff) + ldsw + _i * 8192), 16, 0, 0); } while (0)
; #define PG8_LDA(dst, b, h) do { _Pragma("unroll") for (int m = 0; m < 4; ++m) _Pragma("unroll") for (int k = 0; k < 2; ++k) dst[m][k] = *(const PG8_LAS bf16x8*)(lds + PG8_SA(b, h) + aoff + m * 2048 + k * 1024); } while (0)
; #define PG8_LDB(dst, b, h) do { _Pragma("unroll") for (int n = 0; n < 2; ++n) _Pragma("unroll") for (int k = 0; k < 2; ++k) dst[n][k] = *(const PG8_LAS bf16x8*)(lds + PG8_SB(b, h) + boff + n * 2048 + k * 1024); } while (0)
; #define PG8_MMA(ai, bj, At, Bt) do { __builtin_amdgcn_s_setprio(1); _Pragma("unroll") for (int m = 0; m < 4; ++m) _Pragma("unroll") for (int n = 0; n < 2; ++n) _Pragma("unroll") for (int k = 0; k < 2; ++k) \
;         acc[ai][bj][m][n] = __builtin_amdgcn_mfma_f32_16x16x32_bf16(Bt[n][k], At[m][k], acc[ai][bj][m][n], 0, 0, 0); __builtin_amdgcn_s_setprio(0); } while (0)
; #define PG8_WAIT_V(n) asm volatile("s_waitcnt vmcnt(" #n ")" ::: "memory")
; #define PG8_WAIT_L(n) asm volatile("s_waitcnt lgkmcnt(" #n ")" ::: "memory")
; #define PG8_BAR __builtin_amdgcn_s_barrier()
; #define PG8_SCHED __builtin_amdgcn_sched_barrier(0)
; template <class Epi, class Sched, bool ALIGN_EPI = false, bool SP2 = false>
; __device__ __forceinline__ void gemm_phase(PG8_LAS unsigned char* lds, const Gemm g, const Sched& S, const Epi& E, const int tid) {
;     ...
;             PG8_LDB(B0, 1, 0); PG8_LDB(B1, 1, 1); PG8_SCHED; PG8_LDA(At, 1, 0); PG8_STAGE(PG8_SA(0, 1), a2 + hstep, voffA);
;             PG8_WAIT_V(8); PG8_WAIT_L(0); PG8_BAR; PG8_MMA(0, 0, At, B0); PG8_MMA(0, 1, At, B1); PG8_BAR; PG8_SCHED;
;             PG8_LDA(At, 1, 1); PG8_STAGE(PG8_SB(1, 0), b3, voffB); PG8_STAGE(PG8_SB(1, 1), b3 + hstep, voffB); PG8_STAGE(PG8_SA(1, 0), a3, voffA);
;             PG8_WAIT_V(8); PG8_WAIT_L(0); PG8_BAR; PG8_MMA(1, 0, At, B0); PG8_MMA(1, 1, At, B1); PG8_BAR; PG8_SCHED;
;     ...
;         if constexpr (ALIGN_EPI) { if (wr == 0) PG8_BAR; }
.Lres_mid:
	s_add_i32 s82, 0, 0x18000
	s_add_i32 s85, 0, 0x1c000
	v_add_u32_e32 v68, s82, v181
	v_add_u32_e32 v156, s85, v181
	ds_read_b128 v[48:51], v68
	ds_read_b128 v[52:55], v68 offset:1024
	ds_read_b128 v[64:67], v68 offset:2048
	ds_read_b128 v[68:71], v68 offset:3072
	ds_read_b128 v[144:147], v156
	ds_read_b128 v[148:151], v156 offset:1024
	ds_read_b128 v[152:155], v156 offset:2048
	ds_read_b128 v[156:159], v156 offset:3072
	s_add_u32 s54, s54, s90
	s_addc_u32 s55, s55, 0
	s_mov_b32 m0, s49
	v_lshl_add_u64 v[166:167], s[54:55], 0, v[164:165]
	ds_read_b128 v[188:191], v218 offset:32768
	ds_read_b128 v[192:195], v218 offset:33792
	ds_read_b128 v[196:199], v218 offset:34816
	ds_read_b128 v[222:225], v218 offset:35840
	ds_read_b128 v[226:229], v218 offset:36864
	ds_read_b128 v[230:233], v218 offset:37888
	ds_read_b128 v[234:237], v218 offset:38912
	ds_read_b128 v[238:241], v218 offset:39936
	global_load_lds_dwordx4 v[166:167], off
	v_lshl_add_u64 v[166:167], s[54:55], 0, v[160:161]
	s_mov_b32 m0, s50
	s_nop 0
	global_load_lds_dwordx4 v[166:167], off
	s_waitcnt vmcnt(8)
	s_waitcnt lgkmcnt(0)
	s_barrier
	s_waitcnt lgkmcnt(0)
	v_mfma_f32_16x16x32_bf16 v[140:143], v[48:51], v[188:191], v[140:143]
	v_mfma_f32_16x16x32_bf16 v[136:139], v[64:67], v[188:191], v[136:139]
	v_mfma_f32_16x16x32_bf16 v[124:127], v[48:51], v[196:199], v[124:127]
	v_mfma_f32_16x16x32_bf16 v[120:123], v[64:67], v[196:199], v[120:123]
	v_mfma_f32_16x16x32_bf16 v[108:111], v[48:51], v[226:229], v[108:111]
	v_mfma_f32_16x16x32_bf16 v[104:107], v[64:67], v[226:229], v[104:107]
	v_mfma_f32_16x16x32_bf16 v[92:95], v[48:51], v[234:237], v[92:95]
	v_mfma_f32_16x16x32_bf16 v[88:91], v[64:67], v[234:237], v[88:91]
	v_mfma_f32_16x16x32_bf16 v[140:143], v[52:55], v[192:195], v[140:143]
	v_mfma_f32_16x16x32_bf16 v[136:139], v[68:71], v[192:195], v[136:139]
	v_mfma_f32_16x16x32_bf16 v[124:127], v[52:55], v[222:225], v[124:127]
	v_mfma_f32_16x16x32_bf16 v[120:123], v[68:71], v[222:225], v[120:123]
	v_mfma_f32_16x16x32_bf16 v[108:111], v[52:55], v[230:233], v[108:111]
	v_mfma_f32_16x16x32_bf16 v[104:107], v[68:71], v[230:233], v[104:107]
	v_mfma_f32_16x16x32_bf16 v[92:95], v[52:55], v[238:241], v[92:95]
	v_mfma_f32_16x16x32_bf16 v[88:91], v[68:71], v[238:241], v[88:91]
	v_mfma_f32_16x16x32_bf16 v[132:135], v[144:147], v[188:191], v[132:135]
	v_mfma_f32_16x16x32_bf16 v[128:131], v[152:155], v[188:191], v[128:131]
	v_mfma_f32_16x16x32_bf16 v[116:119], v[144:147], v[196:199], v[116:119]
	v_mfma_f32_16x16x32_bf16 v[112:115], v[152:155], v[196:199], v[112:115]
	v_mfma_f32_16x16x32_bf16 v[100:103], v[144:147], v[226:229], v[100:103]
	v_mfma_f32_16x16x32_bf16 v[96:99], v[152:155], v[226:229], v[96:99]
	v_mfma_f32_16x16x32_bf16 v[84:87], v[144:147], v[234:237], v[84:87]
	v_mfma_f32_16x16x32_bf16 v[80:83], v[152:155], v[234:237], v[80:83]
	v_mfma_f32_16x16x32_bf16 v[132:135], v[148:151], v[192:195], v[132:135]
	v_mfma_f32_16x16x32_bf16 v[128:131], v[156:159], v[192:195], v[128:131]
	v_mfma_f32_16x16x32_bf16 v[116:119], v[148:151], v[222:225], v[116:119]
	v_mfma_f32_16x16x32_bf16 v[112:115], v[156:159], v[222:225], v[112:115]
	v_mfma_f32_16x16x32_bf16 v[100:103], v[148:151], v[230:233], v[100:103]
	v_mfma_f32_16x16x32_bf16 v[96:99], v[156:159], v[230:233], v[96:99]
	v_mfma_f32_16x16x32_bf16 v[84:87], v[148:151], v[238:241], v[84:87]
	v_mfma_f32_16x16x32_bf16 v[80:83], v[156:159], v[238:241], v[80:83]
	s_barrier
	s_add_i32 s54, s82, s38
	v_lshl_add_u64 v[166:167], v[200:201], 0, s[86:87]
	s_mov_b32 m0, s54
	ds_read_b128 v[188:191], v218 offset:49152
	ds_read_b128 v[192:195], v218 offset:50176
	ds_read_b128 v[196:199], v218 offset:51200
	ds_read_b128 v[222:225], v218 offset:52224
	ds_read_b128 v[226:229], v218 offset:53248
	ds_read_b128 v[230:233], v218 offset:54272
	ds_read_b128 v[234:237], v218 offset:55296
	ds_read_b128 v[238:241], v218 offset:56320
	global_load_lds_dwordx4 v[166:167], off
	v_lshl_add_u64 v[166:167], v[242:243], 0, s[86:87]
	s_add_i32 m0, s54, 0x2000
	s_add_i32 s54, s85, s38
	global_load_lds_dwordx4 v[166:167], off
	v_lshl_add_u64 v[166:167], v[244:245], 0, s[86:87]
	s_mov_b32 m0, s54
	s_nop 0
	global_load_lds_dwordx4 v[166:167], off
	v_lshl_add_u64 v[166:167], v[246:247], 0, s[86:87]
	s_add_i32 m0, s54, 0x2000
	s_nop 0
	global_load_lds_dwordx4 v[166:167], off
	v_lshl_add_u64 v[166:167], v[248:249], 0, s[86:87]
	s_mov_b32 m0, s57
	s_nop 0
	global_load_lds_dwordx4 v[166:167], off
	v_lshl_add_u64 v[166:167], v[250:251], 0, s[86:87]
	s_mov_b32 m0, s58
	s_nop 0
	global_load_lds_dwordx4 v[166:167], off
	s_waitcnt vmcnt(8)
	s_waitcnt lgkmcnt(0)
	s_barrier
	s_waitcnt lgkmcnt(0)
	v_mfma_f32_16x16x32_bf16 v[76:79], v[48:51], v[188:191], v[76:79]
	v_mfma_f32_16x16x32_bf16 v[72:75], v[64:67], v[188:191], v[72:75]
	v_mfma_f32_16x16x32_bf16 v[60:63], v[48:51], v[196:199], v[60:63]
	v_mfma_f32_16x16x32_bf16 v[56:59], v[64:67], v[196:199], v[56:59]
	v_mfma_f32_16x16x32_bf16 v[28:31], v[48:51], v[226:229], v[28:31]
	v_mfma_f32_16x16x32_bf16 v[24:27], v[64:67], v[226:229], v[24:27]
	v_mfma_f32_16x16x32_bf16 v[12:15], v[48:51], v[234:237], v[12:15]
	v_mfma_f32_16x16x32_bf16 v[8:11], v[64:67], v[234:237], v[8:11]
	v_mfma_f32_16x16x32_bf16 v[76:79], v[52:55], v[192:195], v[76:79]
	v_mfma_f32_16x16x32_bf16 v[72:75], v[68:71], v[192:195], v[72:75]
	v_mfma_f32_16x16x32_bf16 v[60:63], v[52:55], v[222:225], v[60:63]
	v_mfma_f32_16x16x32_bf16 v[56:59], v[68:71], v[222:225], v[56:59]
	v_mfma_f32_16x16x32_bf16 v[28:31], v[52:55], v[230:233], v[28:31]
	v_mfma_f32_16x16x32_bf16 v[24:27], v[68:71], v[230:233], v[24:27]
	v_mfma_f32_16x16x32_bf16 v[12:15], v[52:55], v[238:241], v[12:15]
	v_mfma_f32_16x16x32_bf16 v[8:11], v[68:71], v[238:241], v[8:11]
	v_mfma_f32_16x16x32_bf16 v[32:35], v[144:147], v[188:191], v[32:35]
	v_mfma_f32_16x16x32_bf16 v[68:71], v[148:151], v[192:195], v[32:35]
	v_mfma_f32_16x16x32_bf16 v[32:35], v[152:155], v[188:191], v[36:39]
	v_mfma_f32_16x16x32_bf16 v[64:67], v[156:159], v[192:195], v[32:35]
	v_mfma_f32_16x16x32_bf16 v[32:35], v[144:147], v[196:199], v[44:47]
	v_mfma_f32_16x16x32_bf16 v[44:47], v[148:151], v[222:225], v[32:35]
	v_mfma_f32_16x16x32_bf16 v[32:35], v[152:155], v[196:199], v[40:43]
	v_mfma_f32_16x16x32_bf16 v[20:23], v[144:147], v[226:229], v[20:23]
	v_mfma_f32_16x16x32_bf16 v[16:19], v[152:155], v[226:229], v[16:19]
	v_mfma_f32_16x16x32_bf16 v[4:7], v[144:147], v[234:237], v[4:7]
	v_mfma_f32_16x16x32_bf16 v[0:3], v[152:155], v[234:237], v[0:3]
	v_mfma_f32_16x16x32_bf16 v[40:43], v[156:159], v[222:225], v[32:35]
	v_mfma_f32_16x16x32_bf16 v[20:23], v[148:151], v[230:233], v[20:23]
	v_mfma_f32_16x16x32_bf16 v[16:19], v[156:159], v[230:233], v[16:19]
	v_mfma_f32_16x16x32_bf16 v[4:7], v[148:151], v[238:241], v[4:7]
	v_mfma_f32_16x16x32_bf16 v[0:3], v[156:159], v[238:241], v[0:3]
	s_barrier
	s_add_u32 s73, s73, 0x100
	s_addc_u32 s81, s81, 0
	s_add_u32 s8, s8, 0x100
	s_addc_u32 s9, s9, 0
	s_cmp_ge_u32 s84, s60
	s_mov_b32 s54, s84
	s_cbranch_scc0 .LBB0_1305
	s_and_b64 vcc, exec, s[18:19]
	s_cbranch_vccz .LBB0_1308
	s_barrier

; #define PG8_STAGE(bufoff, gbase, voff) do { _Pragma("unroll") for (int _i = 0; _i < 2; ++_i) \
;         __builtin_amdgcn_global_load_lds((const unsigned*)((const char*)(gbase) + (voff)[_i]), (PG8_LAS unsigned*)(lds + (bufoff) + ldsw + _i * 8192), 16, 0, 0); } while (0)
; #define PG8_LDA(dst, b, h) do { _Pragma("unroll") for (int m = 0; m < 4; ++m) _Pragma("unroll") for (int k = 0; k < 2; ++k) dst[m][k] = *(const PG8_LAS bf16x8*)(lds + PG8_SA(b, h) + aoff + m * 2048 + k * 1024); } while (0)
; #define PG8_LDB(dst, b, h) do { _Pragma("unroll") for (int n = 0; n < 2; ++n) _Pragma("unroll") for (int k = 0; k < 2; ++k) dst[n][k] = *(const PG8_LAS bf16x8*)(lds + PG8_SB(b, h) + boff + n * 2048 + k * 1024); } while (0)
; #define PG8_MMA(ai, bj, At, Bt) do { __builtin_amdgcn_s_setprio(1); _Pragma("unroll") for (int m = 0; m < 4; ++m) _Pragma("unroll") for (int n = 0; n < 2; ++n) _Pragma("unroll") for (int k = 0; k < 2; ++k) \
;         acc[ai][bj][m][n] = __builtin_amdgcn_mfma_f32_16x16x32_bf16(Bt[n][k], At[m][k], acc[ai][bj][m][n], 0, 0, 0); __builtin_amdgcn_s_setprio(0); } while (0)
; #define PG8_WAIT_V(n) asm volatile("s_waitcnt vmcnt(" #n ")" ::: "memory")
; #define PG8_WAIT_L(n) asm volatile("s_waitcnt lgkmcnt(" #n ")" ::: "memory")
; template <class Epi, class Sched, bool ALIGN_EPI = false, bool SP2 = false>
; __device__ __forceinline__ void gemm_phase(PG8_LAS unsigned char* lds, const Gemm g, const Sched& S, const Epi& E, const int tid) {
;     ...
;         const bool has_next = S.next(ui + 1, nxt);
;         const char* nA = has_next ? (const char*)g.A + (size_t)nxt.pm * tstep : cA; const char* nB = has_next ? (const char*)g.Bt + (size_t)nxt.pn * tstep : cB;
;         for (int t = 0; t < nt; t += 2) {
;             const bool last = (t == nt - 2);
;             const char* a1 = cA + (size_t)(t + 1) * kstep;
;             const char* a2 = last ? nA : cA + (size_t)(t + 2) * kstep; const char* b2 = last ? nB : cB + (size_t)(t + 2) * kstep;
;             const char* a3 = a2 + kstep; const char* b3 = b2 + kstep;
;             if (last && has_next) S.a_ready(nxt);
;             if constexpr (SP2) {
;             PG8_LDB(B0, 0, 0); PG8_LDB(B1, 0, 1); PG8_SCHED; PG8_LDA(At, 0, 0); PG8_STAGE(PG8_SA(1, 1), a1 + hstep, voffA);
;             PG8_WAIT_V(8); PG8_WAIT_L(0); PG8_BAR; PG8_MMA(0, 0, At, B0); PG8_MMA(0, 1, At, B1); PG8_BAR; PG8_SCHED;
.LBB0_1491:
	s_ashr_i32 s11, s10, 31
	s_lshl_b64 s[12:13], s[10:11], 19
	s_add_u32 s12, s88, s12
	s_addc_u32 s13, s89, s13
	s_and_b64 s[14:15], s[4:5], exec
	s_cselect_b32 s11, s13, s21
	s_cselect_b32 s55, s12, s20
	s_ashr_i32 s9, s8, 31
	s_lshl_b64 s[14:15], s[8:9], 19
	s_add_u32 s14, s37, s14
	s_addc_u32 s15, s38, s15
	s_and_b64 s[52:53], s[4:5], exec
	s_cselect_b32 s9, s15, s19
	s_cselect_b32 s56, s14, s18
	s_add_u32 s57, s18, 0x100
	s_addc_u32 s58, s19, 0
	s_add_u32 s18, s20, 0x40080
	s_addc_u32 s19, s21, 0
	s_mov_b32 s59, -2
	s_add_u32 s20, s18, 0xfffc0080
	s_addc_u32 s21, s19, -1
	s_add_i32 s60, 0, 0x10000
	s_cmp_eq_u32 s59, 12
	s_cselect_b32 s53, s11, s21
	s_cselect_b32 s52, s55, s20
	s_cselect_b32 s21, s9, s58
	s_cselect_b32 s20, s56, s57
	s_add_i32 s62, 0, 0x14000
	v_add_u32_e32 v154, s60, v143
	v_add_u32_e32 v162, s62, v143
	ds_read_b128 v[138:141], v154
	ds_read_b128 v[146:149], v154 offset:1024
	ds_read_b128 v[150:153], v154 offset:2048
	ds_read_b128 v[154:157], v154 offset:3072
	ds_read_b128 v[158:161], v162
	ds_read_b128 v[180:183], v162 offset:1024
	ds_read_b128 v[184:187], v162 offset:2048
	ds_read_b128 v[188:191], v162 offset:3072
	v_lshl_add_u64 v[162:163], s[18:19], 0, v[136:137]
	s_add_i32 m0, s43, 0xc000
	ds_read_b128 v[192:195], v145
	ds_read_b128 v[196:199], v145 offset:1024
	ds_read_b128 v[214:217], v145 offset:2048
	ds_read_b128 v[218:221], v145 offset:3072
	ds_read_b128 v[222:225], v145 offset:4096
	ds_read_b128 v[226:229], v145 offset:5120
	ds_read_b128 v[230:233], v145 offset:6144
	ds_read_b128 v[234:237], v145 offset:7168
	global_load_lds_dwordx4 v[162:163], off
	v_lshl_add_u64 v[162:163], s[18:19], 0, v[134:135]
	s_add_i32 m0, s43, 0xe000
	s_nop 0
	global_load_lds_dwordx4 v[162:163], off
	s_waitcnt vmcnt(8)
	s_waitcnt lgkmcnt(0)
	s_barrier
	s_waitcnt lgkmcnt(0)
	v_mfma_f32_16x16x32_bf16 v[124:127], v[138:141], v[192:195], 0
	v_mfma_f32_16x16x32_bf16 v[116:119], v[150:153], v[192:195], 0
	v_mfma_f32_16x16x32_bf16 v[108:111], v[138:141], v[214:217], 0
	v_mfma_f32_16x16x32_bf16 v[100:103], v[150:153], v[214:217], 0
	v_mfma_f32_16x16x32_bf16 v[92:95], v[138:141], v[222:225], 0
	v_mfma_f32_16x16x32_bf16 v[84:87], v[150:153], v[222:225], 0
	v_mfma_f32_16x16x32_bf16 v[76:79], v[138:141], v[230:233], 0
	v_mfma_f32_16x16x32_bf16 v[68:71], v[150:153], v[230:233], 0
	v_mfma_f32_16x16x32_bf16 v[124:127], v[146:149], v[196:199], v[124:127]
	v_mfma_f32_16x16x32_bf16 v[116:119], v[154:157], v[196:199], v[116:119]
	v_mfma_f32_16x16x32_bf16 v[108:111], v[146:149], v[218:221], v[108:111]
	v_mfma_f32_16x16x32_bf16 v[100:103], v[154:157], v[218:221], v[100:103]
	v_mfma_f32_16x16x32_bf16 v[92:95], v[146:149], v[226:229], v[92:95]
	v_mfma_f32_16x16x32_bf16 v[84:87], v[154:157], v[226:229], v[84:87]
	v_mfma_f32_16x16x32_bf16 v[76:79], v[146:149], v[234:237], v[76:79]
	v_mfma_f32_16x16x32_bf16 v[68:71], v[154:157], v[234:237], v[68:71]
	v_mfma_f32_16x16x32_bf16 v[120:123], v[158:161], v[192:195], 0
	v_mfma_f32_16x16x32_bf16 v[112:115], v[184:187], v[192:195], 0
	v_mfma_f32_16x16x32_bf16 v[104:107], v[158:161], v[214:217], 0
	v_mfma_f32_16x16x32_bf16 v[96:99], v[184:187], v[214:217], 0
	v_mfma_f32_16x16x32_bf16 v[88:91], v[158:161], v[222:225], 0
	v_mfma_f32_16x16x32_bf16 v[80:83], v[184:187], v[222:225], 0
	v_mfma_f32_16x16x32_bf16 v[72:75], v[158:161], v[230:233], 0
	v_mfma_f32_16x16x32_bf16 v[64:67], v[184:187], v[230:233], 0
	v_mfma_f32_16x16x32_bf16 v[120:123], v[180:183], v[196:199], v[120:123]
	v_mfma_f32_16x16x32_bf16 v[112:115], v[188:191], v[196:199], v[112:115]
	v_mfma_f32_16x16x32_bf16 v[104:107], v[180:183], v[218:221], v[104:107]
	v_mfma_f32_16x16x32_bf16 v[96:99], v[188:191], v[218:221], v[96:99]
	v_mfma_f32_16x16x32_bf16 v[88:91], v[180:183], v[226:229], v[88:91]
	v_mfma_f32_16x16x32_bf16 v[80:83], v[188:191], v[226:229], v[80:83]
	v_mfma_f32_16x16x32_bf16 v[72:75], v[180:183], v[234:237], v[72:75]
	v_mfma_f32_16x16x32_bf16 v[64:67], v[188:191], v[234:237], v[64:67]
	s_barrier
; #define PG8_STAGE(bufoff, gbase, voff) do { _Pragma("unroll") for (int _i = 0; _i < 2; ++_i) \
;         __builtin_amdgcn_global_load_lds((const unsigned*)((const char*)(gbase) + (voff)[_i]), (PG8_LAS unsigned*)(lds + (bufoff) + ldsw + _i * 8192), 16, 0, 0); } while (0)
; #define PG8_LDA(dst, b, h) do { _Pragma("unroll") for (int m = 0; m < 4; ++m) _Pragma("unroll") for (int k = 0; k < 2; ++k) dst[m][k] = *(const PG8_LAS bf16x8*)(lds + PG8_SA(b, h) + aoff + m * 2048 + k * 1024); } while (0)
; #define PG8_MMA(ai, bj, At, Bt) do { __builtin_amdgcn_s_setprio(1); _Pragma("unroll") for (int m = 0; m < 4; ++m) _Pragma("unroll") for (int n = 0; n < 2; ++n) _Pragma("unroll") for (int k = 0; k < 2; ++k) \
;         acc[ai][bj][m][n] = __builtin_amdgcn_mfma_f32_16x16x32_bf16(Bt[n][k], At[m][k], acc[ai][bj][m][n], 0, 0, 0); __builtin_amdgcn_s_setprio(0); } while (0)
; #define PG8_WAIT_V(n) asm volatile("s_waitcnt vmcnt(" #n ")" ::: "memory")
; #define PG8_WAIT_L(n) asm volatile("s_waitcnt lgkmcnt(" #n ")" ::: "memory")
; #define PG8_BAR __builtin_amdgcn_s_barrier()
; #define PG8_SCHED __builtin_amdgcn_sched_barrier(0)
; template <class Epi, class Sched, bool ALIGN_EPI = false, bool SP2 = false>
; __device__ __forceinline__ void gemm_phase(PG8_LAS unsigned char* lds, const Gemm g, const Sched& S, const Epi& E, const int tid) {
;     ...
;             PG8_LDA(At, 0, 1); PG8_STAGE(PG8_SB(0, 0), b2, voffB); PG8_STAGE(PG8_SB(0, 1), b2 + hstep, voffB); PG8_STAGE(PG8_SA(0, 0), a2, voffA);
;             PG8_WAIT_V(8); PG8_WAIT_L(0); PG8_BAR; PG8_MMA(1, 0, At, B0); PG8_MMA(1, 1, At, B1); PG8_BAR; PG8_SCHED;
	s_add_i32 s60, s60, s41
	v_lshl_add_u64 v[162:163], s[20:21], 0, v[164:165]
	s_mov_b32 m0, s60
	ds_read_b128 v[192:195], v145 offset:16384
	ds_read_b128 v[196:199], v145 offset:17408
	ds_read_b128 v[214:217], v145 offset:18432
	ds_read_b128 v[218:221], v145 offset:19456
	ds_read_b128 v[222:225], v145 offset:20480
	ds_read_b128 v[226:229], v145 offset:21504
	ds_read_b128 v[230:233], v145 offset:22528
	ds_read_b128 v[234:237], v145 offset:23552
	global_load_lds_dwordx4 v[162:163], off
	s_add_i32 m0, s60, 0x2000
	s_add_u32 s60, s20, 0x40000
	v_lshl_add_u64 v[200:201], s[20:21], 0, v[128:129]
	s_addc_u32 s61, s21, 0
	s_add_i32 s62, s62, s41
	global_load_lds_dwordx4 v[200:201], off
	v_lshl_add_u64 v[238:239], s[60:61], 0, v[164:165]
	s_mov_b32 m0, s62
	v_lshl_add_u64 v[240:241], s[52:53], 0, v[130:131]
	global_load_lds_dwordx4 v[238:239], off
	v_lshl_add_u64 v[238:239], s[60:61], 0, v[128:129]
	s_add_i32 m0, s62, 0x2000
	s_nop 0
	global_load_lds_dwordx4 v[238:239], off
	v_lshl_add_u64 v[238:239], s[52:53], 0, v[132:133]
	s_mov_b32 m0, s43
	s_nop 0
	global_load_lds_dwordx4 v[238:239], off
	s_mov_b32 m0, s44
	s_nop 0
	global_load_lds_dwordx4 v[240:241], off
	s_waitcnt vmcnt(8)
	s_waitcnt lgkmcnt(0)
	s_barrier
	s_waitcnt lgkmcnt(0)
	v_mfma_f32_16x16x32_bf16 v[60:63], v[138:141], v[192:195], 0
	v_mfma_f32_16x16x32_bf16 v[52:55], v[150:153], v[192:195], 0
	v_mfma_f32_16x16x32_bf16 v[44:47], v[138:141], v[214:217], 0
	v_mfma_f32_16x16x32_bf16 v[36:39], v[150:153], v[214:217], 0
	v_mfma_f32_16x16x32_bf16 v[28:31], v[138:141], v[222:225], 0
	v_mfma_f32_16x16x32_bf16 v[20:23], v[150:153], v[222:225], 0
	v_mfma_f32_16x16x32_bf16 v[12:15], v[138:141], v[230:233], 0
	v_mfma_f32_16x16x32_bf16 v[4:7], v[150:153], v[230:233], 0
	v_mfma_f32_16x16x32_bf16 v[60:63], v[146:149], v[196:199], v[60:63]
	v_mfma_f32_16x16x32_bf16 v[52:55], v[154:157], v[196:199], v[52:55]
	v_mfma_f32_16x16x32_bf16 v[44:47], v[146:149], v[218:221], v[44:47]
	v_mfma_f32_16x16x32_bf16 v[36:39], v[154:157], v[218:221], v[36:39]
	v_mfma_f32_16x16x32_bf16 v[28:31], v[146:149], v[226:229], v[28:31]
	v_mfma_f32_16x16x32_bf16 v[20:23], v[154:157], v[226:229], v[20:23]
	v_mfma_f32_16x16x32_bf16 v[12:15], v[146:149], v[234:237], v[12:15]
	v_mfma_f32_16x16x32_bf16 v[4:7], v[154:157], v[234:237], v[4:7]
	v_mfma_f32_16x16x32_bf16 v[56:59], v[158:161], v[192:195], 0
	v_mfma_f32_16x16x32_bf16 v[48:51], v[184:187], v[192:195], 0
	v_mfma_f32_16x16x32_bf16 v[40:43], v[158:161], v[214:217], 0
	v_mfma_f32_16x16x32_bf16 v[32:35], v[184:187], v[214:217], 0
	v_mfma_f32_16x16x32_bf16 v[24:27], v[158:161], v[222:225], 0
	v_mfma_f32_16x16x32_bf16 v[16:19], v[184:187], v[222:225], 0
	v_mfma_f32_16x16x32_bf16 v[8:11], v[158:161], v[230:233], 0
	v_mfma_f32_16x16x32_bf16 v[0:3], v[184:187], v[230:233], 0
	v_mfma_f32_16x16x32_bf16 v[56:59], v[180:183], v[196:199], v[56:59]
	v_mfma_f32_16x16x32_bf16 v[48:51], v[188:191], v[196:199], v[48:51]
	v_mfma_f32_16x16x32_bf16 v[40:43], v[180:183], v[218:221], v[40:43]
	v_mfma_f32_16x16x32_bf16 v[32:35], v[188:191], v[218:221], v[32:35]
	v_mfma_f32_16x16x32_bf16 v[24:27], v[180:183], v[226:229], v[24:27]
	v_mfma_f32_16x16x32_bf16 v[16:19], v[188:191], v[226:229], v[16:19]
	v_mfma_f32_16x16x32_bf16 v[8:11], v[180:183], v[234:237], v[8:11]
	v_mfma_f32_16x16x32_bf16 v[0:3], v[188:191], v[234:237], v[0:3]
	s_barrier
	s_branch .Lsw_mid

; #define PG8_STAGE(bufoff, gbase, voff) do { _Pragma("unroll") for (int _i = 0; _i < 2; ++_i) \
;         __builtin_amdgcn_global_load_lds((const unsigned*)((const char*)(gbase) + (voff)[_i]), (PG8_LAS unsigned*)(lds + (bufoff) + ldsw + _i * 8192), 16, 0, 0); } while (0)
; #define PG8_LDA(dst, b, h) do { _Pragma("unroll") for (int m = 0; m < 4; ++m) _Pragma("unroll") for (int k = 0; k < 2; ++k) dst[m][k] = *(const PG8_LAS bf16x8*)(lds + PG8_SA(b, h) + aoff + m * 2048 + k * 1024); } while (0)
; #define PG8_LDB(dst, b, h) do { _Pragma("unroll") for (int n = 0; n < 2; ++n) _Pragma("unroll") for (int k = 0; k < 2; ++k) dst[n][k] = *(const PG8_LAS bf16x8*)(lds + PG8_SB(b, h) + boff + n * 2048 + k * 1024); } while (0)
; #define PG8_MMA(ai, bj, At, Bt) do { __builtin_amdgcn_s_setprio(1); _Pragma("unroll") for (int m = 0; m < 4; ++m) _Pragma("unroll") for (int n = 0; n < 2; ++n) _Pragma("unroll") for (int k = 0; k < 2; ++k) \
;         acc[ai][bj][m][n] = __builtin_amdgcn_mfma_f32_16x16x32_bf16(Bt[n][k], At[m][k], acc[ai][bj][m][n], 0, 0, 0); __builtin_amdgcn_s_setprio(0); } while (0)
; #define PG8_WAIT_V(n) asm volatile("s_waitcnt vmcnt(" #n ")" ::: "memory")
; #define PG8_WAIT_L(n) asm volatile("s_waitcnt lgkmcnt(" #n ")" ::: "memory")
; #define PG8_BAR __builtin_amdgcn_s_barrier()
; #define PG8_SCHED __builtin_amdgcn_sched_barrier(0)
; template <class Epi, class Sched, bool ALIGN_EPI = false, bool SP2 = false>
; __device__ __forceinline__ void gemm_phase(PG8_LAS unsigned char* lds, const Gemm g, const Sched& S, const Epi& E, const int tid) {
;     ...
;             PG8_LDB(B0, 1, 0); PG8_LDB(B1, 1, 1); PG8_SCHED; PG8_LDA(At, 1, 0); PG8_STAGE(PG8_SA(0, 1), a2 + hstep, voffA);
;             PG8_WAIT_V(8); PG8_WAIT_L(0); PG8_BAR; PG8_MMA(0, 0, At, B0); PG8_MMA(0, 1, At, B1); PG8_BAR; PG8_SCHED;
.Lsw_mid:
	s_add_i32 s60, 0, 0x18000
	s_add_i32 s61, 0, 0x1c000
	v_add_u32_e32 v154, s60, v143
	v_add_u32_e32 v166, s61, v143
	ds_read_b128 v[138:141], v154
	ds_read_b128 v[146:149], v154 offset:1024
	ds_read_b128 v[150:153], v154 offset:2048
	ds_read_b128 v[154:157], v154 offset:3072
	ds_read_b128 v[158:161], v166
	ds_read_b128 v[180:183], v166 offset:1024
	ds_read_b128 v[184:187], v166 offset:2048
	ds_read_b128 v[188:191], v166 offset:3072
	s_add_u32 s52, s52, 0x40000
	s_addc_u32 s53, s53, 0
	s_mov_b32 m0, s45
	v_lshl_add_u64 v[242:243], s[52:53], 0, v[132:133]
	ds_read_b128 v[192:195], v145 offset:32768
	ds_read_b128 v[196:199], v145 offset:33792
	ds_read_b128 v[214:217], v145 offset:34816
	ds_read_b128 v[218:221], v145 offset:35840
	ds_read_b128 v[222:225], v145 offset:36864
	ds_read_b128 v[226:229], v145 offset:37888
	ds_read_b128 v[230:233], v145 offset:38912
	ds_read_b128 v[234:237], v145 offset:39936
	global_load_lds_dwordx4 v[242:243], off
	v_lshl_add_u64 v[242:243], s[52:53], 0, v[130:131]
	s_mov_b32 m0, s48
	s_nop 0
	global_load_lds_dwordx4 v[242:243], off
	s_waitcnt vmcnt(8)
	s_waitcnt lgkmcnt(0)
	s_barrier
	s_waitcnt lgkmcnt(0)
	v_mfma_f32_16x16x32_bf16 v[124:127], v[138:141], v[192:195], v[124:127]
	v_mfma_f32_16x16x32_bf16 v[116:119], v[150:153], v[192:195], v[116:119]
	v_mfma_f32_16x16x32_bf16 v[108:111], v[138:141], v[214:217], v[108:111]
	v_mfma_f32_16x16x32_bf16 v[100:103], v[150:153], v[214:217], v[100:103]
	v_mfma_f32_16x16x32_bf16 v[92:95], v[138:141], v[222:225], v[92:95]
	v_mfma_f32_16x16x32_bf16 v[84:87], v[150:153], v[222:225], v[84:87]
	v_mfma_f32_16x16x32_bf16 v[76:79], v[138:141], v[230:233], v[76:79]
	v_mfma_f32_16x16x32_bf16 v[68:71], v[150:153], v[230:233], v[68:71]
	v_mfma_f32_16x16x32_bf16 v[124:127], v[146:149], v[196:199], v[124:127]
	v_mfma_f32_16x16x32_bf16 v[116:119], v[154:157], v[196:199], v[116:119]
	v_mfma_f32_16x16x32_bf16 v[108:111], v[146:149], v[218:221], v[108:111]
	v_mfma_f32_16x16x32_bf16 v[100:103], v[154:157], v[218:221], v[100:103]
	v_mfma_f32_16x16x32_bf16 v[92:95], v[146:149], v[226:229], v[92:95]
	v_mfma_f32_16x16x32_bf16 v[84:87], v[154:157], v[226:229], v[84:87]
	v_mfma_f32_16x16x32_bf16 v[76:79], v[146:149], v[234:237], v[76:79]
	v_mfma_f32_16x16x32_bf16 v[68:71], v[154:157], v[234:237], v[68:71]
	v_mfma_f32_16x16x32_bf16 v[120:123], v[158:161], v[192:195], v[120:123]
	v_mfma_f32_16x16x32_bf16 v[112:115], v[184:187], v[192:195], v[112:115]
	v_mfma_f32_16x16x32_bf16 v[104:107], v[158:161], v[214:217], v[104:107]
	v_mfma_f32_16x16x32_bf16 v[96:99], v[184:187], v[214:217], v[96:99]
	v_mfma_f32_16x16x32_bf16 v[88:91], v[158:161], v[222:225], v[88:91]
	v_mfma_f32_16x16x32_bf16 v[80:83], v[184:187], v[222:225], v[80:83]
	v_mfma_f32_16x16x32_bf16 v[72:75], v[158:161], v[230:233], v[72:75]
	v_mfma_f32_16x16x32_bf16 v[64:67], v[184:187], v[230:233], v[64:67]
	v_mfma_f32_16x16x32_bf16 v[120:123], v[180:183], v[196:199], v[120:123]
	v_mfma_f32_16x16x32_bf16 v[112:115], v[188:191], v[196:199], v[112:115]
	v_mfma_f32_16x16x32_bf16 v[104:107], v[180:183], v[218:221], v[104:107]
	v_mfma_f32_16x16x32_bf16 v[96:99], v[188:191], v[218:221], v[96:99]
	v_mfma_f32_16x16x32_bf16 v[88:91], v[180:183], v[226:229], v[88:91]
	v_mfma_f32_16x16x32_bf16 v[80:83], v[188:191], v[226:229], v[80:83]
	v_mfma_f32_16x16x32_bf16 v[72:75], v[180:183], v[234:237], v[72:75]
	v_mfma_f32_16x16x32_bf16 v[64:67], v[188:191], v[234:237], v[64:67]
	s_barrier
; #define PG8_STAGE(bufoff, gbase, voff) do { _Pragma("unroll") for (int _i = 0; _i < 2; ++_i) \
;         __builtin_amdgcn_global_load_lds((const unsigned*)((const char*)(gbase) + (voff)[_i]), (PG8_LAS unsigned*)(lds + (bufoff) + ldsw + _i * 8192), 16, 0, 0); } while (0)
; #define PG8_LDA(dst, b, h) do { _Pragma("unroll") for (int m = 0; m < 4; ++m) _Pragma("unroll") for (int k = 0; k < 2; ++k) dst[m][k] = *(const PG8_LAS bf16x8*)(lds + PG8_SA(b, h) + aoff + m * 2048 + k * 1024); } while (0)
; #define PG8_MMA(ai, bj, At, Bt) do { __builtin_amdgcn_s_setprio(1); _Pragma("unroll") for (int m = 0; m < 4; ++m) _Pragma("unroll") for (int n = 0; n < 2; ++n) _Pragma("unroll") for (int k = 0; k < 2; ++k) \
;         acc[ai][bj][m][n] = __builtin_amdgcn_mfma_f32_16x16x32_bf16(Bt[n][k], At[m][k], acc[ai][bj][m][n], 0, 0, 0); __builtin_amdgcn_s_setprio(0); } while (0)
; #define PG8_WAIT_V(n) asm volatile("s_waitcnt vmcnt(" #n ")" ::: "memory")
; #define PG8_WAIT_L(n) asm volatile("s_waitcnt lgkmcnt(" #n ")" ::: "memory")
; #define PG8_BAR __builtin_amdgcn_s_barrier()
; #define PG8_SCHED __builtin_amdgcn_sched_barrier(0)
; template <class Epi, class Sched, bool ALIGN_EPI = false, bool SP2 = false>
; __device__ __forceinline__ void gemm_phase(PG8_LAS unsigned char* lds, const Gemm g, const Sched& S, const Epi& E, const int tid) {
;     ...
;             PG8_LDA(At, 1, 1); PG8_STAGE(PG8_SB(1, 0), b3, voffB); PG8_STAGE(PG8_SB(1, 1), b3 + hstep, voffB); PG8_STAGE(PG8_SA(1, 0), a3, voffA);
;             PG8_WAIT_V(8); PG8_WAIT_L(0); PG8_BAR; PG8_MMA(1, 0, At, B0); PG8_MMA(1, 1, At, B1); PG8_BAR; PG8_SCHED;
;     ...
;         if constexpr (ALIGN_EPI) { if (wr == 0) PG8_BAR; }
	s_add_i32 s52, s60, s41
	v_lshl_add_u64 v[162:163], v[162:163], 0, s[86:87]
	s_mov_b32 m0, s52
	ds_read_b128 v[192:195], v145 offset:49152
	ds_read_b128 v[196:199], v145 offset:50176
	ds_read_b128 v[214:217], v145 offset:51200
	ds_read_b128 v[218:221], v145 offset:52224
	ds_read_b128 v[222:225], v145 offset:53248
	ds_read_b128 v[226:229], v145 offset:54272
	ds_read_b128 v[230:233], v145 offset:55296
	ds_read_b128 v[234:237], v145 offset:56320
	global_load_lds_dwordx4 v[162:163], off
	s_add_i32 m0, s52, 0x2000
	s_add_u32 s20, s20, 0x40080
	v_lshl_add_u64 v[162:163], v[200:201], 0, s[86:87]
	s_addc_u32 s21, s21, 0
	s_add_i32 s52, s61, s41
	global_load_lds_dwordx4 v[162:163], off
	v_lshl_add_u64 v[162:163], s[20:21], 0, v[164:165]
	s_mov_b32 m0, s52
	s_nop 0
	global_load_lds_dwordx4 v[162:163], off
	v_lshl_add_u64 v[162:163], s[20:21], 0, v[128:129]
	s_add_i32 m0, s52, 0x2000
	s_nop 0
	global_load_lds_dwordx4 v[162:163], off
	v_lshl_add_u64 v[162:163], v[238:239], 0, s[86:87]
	s_mov_b32 m0, s49
	s_nop 0
	global_load_lds_dwordx4 v[162:163], off
	v_lshl_add_u64 v[162:163], v[240:241], 0, s[86:87]
	s_mov_b32 m0, s50
	s_nop 0
	global_load_lds_dwordx4 v[162:163], off
	s_waitcnt vmcnt(8)
	s_waitcnt lgkmcnt(0)
	s_barrier
	s_waitcnt lgkmcnt(0)
	v_mfma_f32_16x16x32_bf16 v[60:63], v[138:141], v[192:195], v[60:63]
	v_mfma_f32_16x16x32_bf16 v[52:55], v[150:153], v[192:195], v[52:55]
	v_mfma_f32_16x16x32_bf16 v[44:47], v[138:141], v[214:217], v[44:47]
	v_mfma_f32_16x16x32_bf16 v[36:39], v[150:153], v[214:217], v[36:39]
	v_mfma_f32_16x16x32_bf16 v[28:31], v[138:141], v[222:225], v[28:31]
	v_mfma_f32_16x16x32_bf16 v[20:23], v[150:153], v[222:225], v[20:23]
	v_mfma_f32_16x16x32_bf16 v[12:15], v[138:141], v[230:233], v[12:15]
	v_mfma_f32_16x16x32_bf16 v[4:7], v[150:153], v[230:233], v[4:7]
	v_mfma_f32_16x16x32_bf16 v[60:63], v[146:149], v[196:199], v[60:63]
	v_mfma_f32_16x16x32_bf16 v[52:55], v[154:157], v[196:199], v[52:55]
	v_mfma_f32_16x16x32_bf16 v[44:47], v[146:149], v[218:221], v[44:47]
	v_mfma_f32_16x16x32_bf16 v[36:39], v[154:157], v[218:221], v[36:39]
	v_mfma_f32_16x16x32_bf16 v[28:31], v[146:149], v[226:229], v[28:31]
	v_mfma_f32_16x16x32_bf16 v[20:23], v[154:157], v[226:229], v[20:23]
	v_mfma_f32_16x16x32_bf16 v[12:15], v[146:149], v[234:237], v[12:15]
	v_mfma_f32_16x16x32_bf16 v[4:7], v[154:157], v[234:237], v[4:7]
	v_mfma_f32_16x16x32_bf16 v[56:59], v[158:161], v[192:195], v[56:59]
	v_mfma_f32_16x16x32_bf16 v[48:51], v[184:187], v[192:195], v[48:51]
	v_mfma_f32_16x16x32_bf16 v[40:43], v[158:161], v[214:217], v[40:43]
	v_mfma_f32_16x16x32_bf16 v[32:35], v[184:187], v[214:217], v[32:35]
	v_mfma_f32_16x16x32_bf16 v[24:27], v[158:161], v[222:225], v[24:27]
	v_mfma_f32_16x16x32_bf16 v[16:19], v[184:187], v[222:225], v[16:19]
	v_mfma_f32_16x16x32_bf16 v[8:11], v[158:161], v[230:233], v[8:11]
	v_mfma_f32_16x16x32_bf16 v[0:3], v[184:187], v[230:233], v[0:3]
	v_mfma_f32_16x16x32_bf16 v[56:59], v[180:183], v[196:199], v[56:59]
	v_mfma_f32_16x16x32_bf16 v[48:51], v[188:191], v[196:199], v[48:51]
	v_mfma_f32_16x16x32_bf16 v[40:43], v[180:183], v[218:221], v[40:43]
	v_mfma_f32_16x16x32_bf16 v[32:35], v[188:191], v[218:221], v[32:35]
	v_mfma_f32_16x16x32_bf16 v[24:27], v[180:183], v[226:229], v[24:27]
	v_mfma_f32_16x16x32_bf16 v[16:19], v[188:191], v[226:229], v[16:19]
	v_mfma_f32_16x16x32_bf16 v[8:11], v[180:183], v[234:237], v[8:11]
	v_mfma_f32_16x16x32_bf16 v[0:3], v[188:191], v[234:237], v[0:3]
	s_barrier
	s_add_i32 s59, s59, 2
	s_add_u32 s57, s57, 0x100
	s_addc_u32 s58, s58, 0
	s_add_u32 s18, s18, 0x100
	s_addc_u32 s19, s19, 0
	s_cmp_gt_u32 s59, 13
	s_cbranch_scc0 .LBB0_1492
	s_and_b64 vcc, exec, s[6:7]
	s_cbranch_vccz .LBB0_1495
	s_barrier
